# grid barrier: acquire invalidate issued before the spin (followers) / with the arrival atomic (leaders) so it overlaps the wait instead of following the release
# baseline (speedup 1.0000x reference)
; DI unsigned xb_ld(unsigned* p) { return __hip_atomic_load(p, __ATOMIC_RELAXED, __HIP_MEMORY_SCOPE_AGENT); }
; #define XB_SPIN(cond, bar) do { unsigned _sp = 0; while (cond) { __builtin_amdgcn_s_sleep(1); \
;     if ((++_sp & 255u) == 0u) { if (xb_ld(&(bar)[XB_TMO])) break; if (_sp > XB_SPIN_CAP) { atomicAdd(&(bar)[XB_TMO], 1u); break; } } } } while (0)
; DI void xcd_barrier(unsigned* bar, const unsigned x, volatile LAS unsigned* st, const int tid) {
;     ...
;     } else {
;       XB_SPIN(xb_ld(&bar[XB_XGEN(x)]) == gen, bar);
;       __builtin_amdgcn_fence(__ATOMIC_ACQUIRE, "agent");
;       asm volatile("s_waitcnt vmcnt(0)" ::: "memory");
.LBB0_1279:
	s_or_b64 exec, exec, s[2:3]
	v_cvt_f32_u32_e32 v5, v3
	s_waitcnt vmcnt(0)
	v_readfirstlane_b32 s2, v4
	v_sub_u32_e32 v4, 0, v3
	v_rcp_iflag_f32_e32 v5, v5
	v_add_u32_e32 v6, s2, v0
	v_mul_f32_e32 v5, 0x4f7ffffe, v5
	v_cvt_u32_f32_e32 v5, v5
	v_mul_lo_u32 v0, v4, v5
	v_mul_hi_u32 v0, v5, v0
	v_add_u32_e32 v0, v5, v0
	v_mul_hi_u32 v0, v6, v0
	v_mul_lo_u32 v4, v0, v3
	v_sub_u32_e32 v4, v6, v4
	v_add_u32_e32 v5, 1, v0
	v_cmp_ge_u32_e32 vcc, v4, v3
	s_nop 1
	v_cndmask_b32_e32 v0, v0, v5, vcc
	v_sub_u32_e32 v5, v4, v3
	v_cndmask_b32_e32 v4, v4, v5, vcc
	v_add_u32_e32 v5, 1, v0
	v_cmp_ge_u32_e32 vcc, v4, v3
	v_add_u32_e32 v4, 1, v6
	s_nop 0
	v_cndmask_b32_e32 v0, v0, v5, vcc
	v_mul_lo_u32 v5, v3, v0
	v_add_u32_e32 v3, v5, v3
	v_cmp_ne_u32_e32 vcc, v4, v3
	s_and_saveexec_b64 s[2:3], vcc
	s_xor_b64 s[2:3], exec, s[2:3]
	s_cbranch_execz .LBB0_1293
	buffer_inv sc1
	v_readlane_b32 s4, v252, 56
	v_readlane_b32 s5, v252, 57
	s_waitcnt lgkmcnt(0)
	v_add_u32_e32 v0, 1, v0
	v_mul_lo_u32 v0, v0, v2
	s_nop 3
	global_load_dword v2, v1, s[4:5] sc1
	s_waitcnt vmcnt(0)
	v_cmp_lt_u32_e32 vcc, v2, v0
	s_and_saveexec_b64 s[4:5], vcc
	s_cbranch_execz .LBB0_1292
	s_mov_b32 s16, 1
	s_mov_b64 s[6:7], 0
	s_branch .LBB0_1283

; DI unsigned xb_ld(unsigned* p) { return __hip_atomic_load(p, __ATOMIC_RELAXED, __HIP_MEMORY_SCOPE_AGENT); }
; #define XB_SPIN(cond, bar) do { unsigned _sp = 0; while (cond) { __builtin_amdgcn_s_sleep(1); \
;     if ((++_sp & 255u) == 0u) { if (xb_ld(&(bar)[XB_TMO])) break; if (_sp > XB_SPIN_CAP) { atomicAdd(&(bar)[XB_TMO], 1u); break; } } } } while (0)
; DI void xcd_barrier(unsigned* bar, const unsigned x, volatile LAS unsigned* st, const int tid) {
;     ...
;       XB_SPIN(xb_ld(&bar[XB_XGEN(x)]) == gen, bar);
;       __builtin_amdgcn_fence(__ATOMIC_ACQUIRE, "agent");
;       asm volatile("s_waitcnt vmcnt(0)" ::: "memory");
.LBB0_1292:
	s_or_b64 exec, exec, s[4:5]
	s_waitcnt vmcnt(0)
	s_waitcnt vmcnt(0)

; DI unsigned xb_add(unsigned* p, unsigned v) { return __hip_atomic_fetch_add(p, v, __ATOMIC_RELAXED, __HIP_MEMORY_SCOPE_AGENT); }
; DI void xcd_barrier(unsigned* bar, const unsigned x, volatile LAS unsigned* st, const int tid) {
;     ...
;     if (old + 1u == (gen + 1u) * nloc) {
;       __builtin_amdgcn_fence(__ATOMIC_RELEASE, "agent");
;       asm volatile("s_waitcnt vmcnt(0)" ::: "memory");
;       const unsigned og = xb_add(&bar[XB_TOP], 1u);
.LBB0_1294:
	s_mov_b64 s[2:3], exec
	buffer_wbl2 sc1
	s_waitcnt lgkmcnt(0)
	s_waitcnt vmcnt(0)
	v_mbcnt_lo_u32_b32 v0, s2, 0
	v_mbcnt_hi_u32_b32 v0, s3, v0
	v_cmp_eq_u32_e32 vcc, 0, v0
	s_and_saveexec_b64 s[4:5], vcc
	s_cbranch_execz .LBB0_1296
	s_bcnt1_i32_b64 s2, s[2:3]
	v_mov_b32_e32 v3, s2
	v_readlane_b32 s2, v252, 56
	v_readlane_b32 s3, v252, 57
	s_nop 4
	global_atomic_add v3, v1, v3, s[2:3] sc0
	buffer_inv sc1

; DI unsigned xb_ld(unsigned* p) { return __hip_atomic_load(p, __ATOMIC_RELAXED, __HIP_MEMORY_SCOPE_AGENT); }
; DI unsigned xb_add(unsigned* p, unsigned v) { return __hip_atomic_fetch_add(p, v, __ATOMIC_RELAXED, __HIP_MEMORY_SCOPE_AGENT); }
; #define XB_SPIN(cond, bar) do { unsigned _sp = 0; while (cond) { __builtin_amdgcn_s_sleep(1); \
;     if ((++_sp & 255u) == 0u) { if (xb_ld(&(bar)[XB_TMO])) break; if (_sp > XB_SPIN_CAP) { atomicAdd(&(bar)[XB_TMO], 1u); break; } } } } while (0)
; DI void xcd_barrier(unsigned* bar, const unsigned x, volatile LAS unsigned* st, const int tid) {
;     ...
;       else XB_SPIN(xb_ld(&bar[XB_TOPGEN]) == tg, bar);
;       __builtin_amdgcn_fence(__ATOMIC_ACQUIRE, "agent");
;       xb_add(&bar[XB_XGEN(x)], 1u);
.LBB0_1310:
	s_or_b64 exec, exec, s[2:3]
	s_mov_b64 s[2:3], exec
	v_mbcnt_lo_u32_b32 v0, s2, 0
	v_mbcnt_hi_u32_b32 v0, s3, v0
	v_cmp_eq_u32_e32 vcc, 0, v0
	s_waitcnt vmcnt(0)
	s_and_saveexec_b64 s[4:5], vcc
	s_cbranch_execnz .LBB0_1311
	s_getpc_b64 s[98:99]
